# P0: waves 4-7 run the RMSNorm streaming section before their weight-transpose items so both kinds of work overlap on every SIMD
# baseline (speedup 1.0000x reference)
.LBB0_5:
	s_or_b64 exec, exec, s[0:1]
	v_readlane_b32 s0, v254, 0
	s_lshr_b32 s84, s4, 6
	s_lshl_b32 s0, s0, 3
	s_add_i32 s86, s84, s0
	s_lshl_b32 s42, s92, 3
	s_lshl_b32 s0, s92, 9
	v_writelane_b32 v254, s0, 11
	s_cmp_lt_i32 s82, 1
	v_and_b32_e32 v228, 63, v230
	v_writelane_b32 v254, s1, 12
	s_cselect_b64 s[0:1], -1, 0
	s_cmp_gt_i32 s83, 0
	s_cselect_b64 s[2:3], -1, 0
	s_and_b64 s[0:1], s[0:1], s[2:3]
	s_andn2_b64 vcc, exec, s[0:1]
	s_cbranch_vccnz .LBB0_72
	s_mov_b32 s101, 0
.Lp0_again:
	s_mov_b64 s[8:9], 0
	s_add_u32 s10, s80, s8
	s_addc_u32 s11, s81, s9
	s_cmpk_gt_i32 s86, 0x2a7f
	v_readlane_b32 s2, v254, 0
	v_mov_b32_e32 v1, v230
	s_cbranch_scc1 .LBB0_53
	s_cmp_lg_u32 s101, 0
	s_cbranch_scc1 .Lp0_tr
	s_bitcmp1_b32 s84, 2
	s_cbranch_scc0 .Lp0_tr
	s_mov_b32 s101, 1
	s_branch .LBB0_53
.Lp0_tr:
	s_lshl_b32 s2, s84, 14
	v_and_b32_e32 v9, 31, v230
	v_lshlrev_b32_e32 v1, 3, v230
	s_add_i32 s2, s2, 0
	v_lshlrev_b32_e32 v4, 2, v9
	v_mov_b32_e32 v5, 0
	v_lshrrev_b32_e32 v37, 3, v228
	v_and_b32_e32 v1, 56, v1
	v_lshl_add_u64 v[6:7], s[76:77], 0, v[4:5]
	v_add_u32_e32 v8, s2, v4
	v_mul_u32_u24_e32 v3, 0x84, v1
	v_lshlrev_b32_e32 v39, 2, v37
	v_lshl_add_u64 v[10:11], s[74:75], 0, v[4:5]
	v_lshl_add_u64 v[12:13], s[72:73], 0, v[4:5]
	v_lshl_add_u64 v[14:15], s[70:71], 0, v[4:5]
	v_lshl_add_u64 v[16:17], s[68:69], 0, v[4:5]
	v_lshl_add_u64 v[18:19], s[62:63], 0, v[4:5]
	v_lshl_add_u64 v[20:21], s[50:51], 0, v[4:5]
	v_lshlrev_b32_e32 v4, 1, v1
	v_add3_u32 v40, s2, v3, v39
	v_lshl_add_u64 v[22:23], s[10:11], 0, v[4:5]
	s_mov_b64 s[2:3], 0x2500000
	v_lshl_add_u64 v[24:25], v[22:23], 0, s[2:3]
	s_mov_b64 s[2:3], 0x1a00000
	v_lshl_add_u64 v[26:27], v[22:23], 0, s[2:3]
	s_mov_b64 s[2:3], 0x1800000
	v_lshl_add_u64 v[28:29], v[22:23], 0, s[2:3]
	s_mov_b64 s[2:3], 0x1500000
	v_lshrrev_b32_e32 v2, 5, v228
	v_bfe_u32 v38, v228, 3, 2
	v_lshl_add_u64 v[30:31], v[22:23], 0, s[2:3]
	s_mov_b64 s[2:3], 0x1300000
	s_mov_b32 s5, 0
	s_movk_i32 s14, 0x84
	v_or_b32_e32 v41, 8, v37
	v_or_b32_e32 v42, 16, v37
	v_or_b32_e32 v43, 24, v37
	v_and_b32_e32 v44, 16, v39
	v_lshl_add_u64 v[32:33], v[22:23], 0, s[2:3]
	v_or_b32_e32 v45, 0x800, v38
	v_or_b32_e32 v46, 0x400, v38
	v_mov_b32_e32 v1, v2
	s_movk_i32 s15, 0x1600
	s_movk_i32 s16, 0x63
	s_mov_b32 s17, 0x9800
	s_mov_b32 s18, s86
	s_branch .LBB0_9

.LBB0_53:
	s_cmp_eq_u32 s101, 2
	s_cbranch_scc1 .LBB0_71
	v_readlane_b32 s2, v254, 0
	s_mov_b32 s4, 0x10000
	s_nop 0
	v_lshl_add_u32 v2, s2, 9, v230
	v_cmp_gt_i32_e32 vcc, s4, v2
	s_and_saveexec_b64 s[2:3], vcc
	v_readlane_b32 s16, v254, 11
	v_readlane_b32 s17, v254, 12
	s_cbranch_execz .LBB0_61
	v_cvt_f32_u32_e32 v1, s16
	v_add_u32_e32 v3, s16, v2
	v_mov_b32_e32 v4, s16
	v_cmp_gt_i32_e32 vcc, s4, v3
	v_rcp_iflag_f32_e32 v1, v1
	s_sub_i32 s12, 0, s16
	v_max_i32_e32 v5, 0x10000, v3
	v_addc_co_u32_e64 v4, s[4:5], v2, v4, vcc
	v_mul_f32_e32 v1, 0x4f7ffffe, v1
	v_cvt_u32_f32_e32 v1, v1
	v_sub_u32_e32 v4, v5, v4
	v_mul_lo_u32 v5, s12, v1
	v_mul_hi_u32 v5, v1, v5
	v_add_u32_e32 v1, v1, v5
	v_mul_hi_u32 v1, v4, v1
	v_mul_lo_u32 v5, v1, s16
	v_sub_u32_e32 v4, v4, v5
	v_add_u32_e32 v6, 1, v1
	v_cmp_le_u32_e64 s[4:5], s16, v4
	v_subrev_u32_e32 v5, s16, v4
	s_mov_b64 s[12:13], -1
	v_cndmask_b32_e64 v1, v1, v6, s[4:5]
	v_cndmask_b32_e64 v4, v4, v5, s[4:5]
	v_add_u32_e32 v5, 1, v1
	v_cmp_le_u32_e64 s[4:5], s16, v4
	s_nop 1
	v_cndmask_b32_e64 v1, v1, v5, s[4:5]
	v_addc_co_u32_e32 v1, vcc, 1, v1, vcc
	v_cmp_lt_u32_e32 vcc, 1, v1
	s_and_saveexec_b64 s[4:5], vcc
	s_cbranch_execz .LBB0_58
	s_add_u32 s12, s10, 0x12000000
	s_addc_u32 s13, s11, 0
	v_and_b32_e32 v6, -2, v1
	s_lshl_b32 s16, s92, 10
	s_mov_b32 s17, s16
	s_mov_b64 s[14:15], 0
	v_mov_b32_e32 v7, 0
	v_mov_b32_e32 v8, v6
	v_mov_b64_e32 v[4:5], v[2:3]

.LBB0_71:
	s_cmp_eq_u32 s101, 1
	s_cbranch_scc0 .Lp0_end
	s_mov_b32 s101, 2
	s_branch .Lp0_again

.LBB0_84:
	s_cmp_lt_i32 s82, 2
	s_cselect_b64 s[0:1], -1, 0
	s_and_b64 s[0:1], s[0:1], s[2:3]
	s_andn2_b64 vcc, exec, s[0:1]
	s_cbranch_vccnz .LBB0_105
	s_mov_b64 s[2:3], 0
	v_readlane_b32 s26, v254, 0
	v_mov_b32_e32 v0, v230
	v_mov_b32_e32 v8, v230
	s_cmpk_gt_i32 s26, 0x7f
	v_readfirstlane_b32 s27, v8
	s_cbranch_scc1 .LBB0_105
	s_ashr_i32 s28, s26, 31
	s_lshr_b32 s4, s28, 29
	s_add_i32 s8, s26, s4
	s_and_b32 s4, s8, -8
	s_sub_i32 s6, s26, s4
	s_cmp_gt_i32 s6, -1
	s_cbranch_scc0 .LBB0_88
	s_lshl_b32 s7, s6, 4
	s_ashr_i32 s4, s8, 3
	s_cbranch_execz .LBB0_89
	s_branch .LBB0_90
	s_nop 0
	s_nop 0
	s_nop 0
	s_nop 0
	s_nop 0
	s_nop 0
	s_nop 0
	s_nop 0
	s_nop 0
	s_nop 0
	s_nop 0
